# conv redistribution 4/32 slots (heavy/light) instead of 8/28
# baseline (speedup 1.0000x reference)
; __device__ __forceinline__ void conv_phase(bf16_t* proj, const float* cw, int G) {
;     int tid_ = threadIdx.x; asm volatile("" : "+v"(tid_));
;     for (int item = blockIdx.x * 512 + tid_; item < M * 48; item += G * 512) {
;         const int row = item / 48, ch = (item % 48) * 8, t = row % SEQ;
; __device__ __forceinline__ void attn_phase(unsigned char* ws, int l, LAS unsigned char* lds, int G) {
;     ...
;     const int vb = (G % 8 == 0) ? (bx % 8) * (G / 8) + bx / 8 : bx;
.LBB0_561:
	v_mov_b32_e32 v0, v154
	s_lshl_b32 s33, s14, 9
	s_lshl_b32 s95, s14, 9
	s_mov_b32 s93, 0x240000
	s_lshl_b32 s94, s74, 9
	s_cmpk_lg_u32 s74, 0x100
	s_cbranch_scc1 .Lcv0_go
	s_and_b32 s92, s14, 7
	s_lshl_b32 s92, s92, 5
	s_lshr_b32 s95, s14, 3
	s_add_i32 s92, s92, s95
	s_mov_b32 s94, 0x10000
	s_cmpk_lt_u32 s92, 0x80
	s_cbranch_scc1 .Lcv0_heavy
	s_addk_i32 s92, 384
	s_lshl_b32 s95, s92, 9
	s_branch .Lcv0_go
.Lcv0_heavy:
	s_lshl_b32 s95, s92, 9
	s_mov_b32 s93, 0x40000

; __device__ __forceinline__ void conv_phase(bf16_t* proj, const float* cw, int G) {
;     int tid_ = threadIdx.x; asm volatile("" : "+v"(tid_));
;     for (int item = blockIdx.x * 512 + tid_; item < M * 48; item += G * 512) {
;         const int row = item / 48, ch = (item % 48) * 8, t = row % SEQ;
; __device__ __forceinline__ void attn_phase(unsigned char* ws, int l, LAS unsigned char* lds, int G) {
;     ...
;     const int vb = (G % 8 == 0) ? (bx % 8) * (G / 8) + bx / 8 : bx;
.LBB0_1273:
	v_mov_b32_e32 v0, v154
	s_lshl_b32 s95, s14, 9
	s_mov_b32 s93, 0x240000
	s_lshl_b32 s94, s74, 9
	s_cmpk_lg_u32 s74, 0x100
	s_cbranch_scc1 .Lcv1_go
	s_and_b32 s92, s14, 7
	s_lshl_b32 s92, s92, 5
	s_lshr_b32 s95, s14, 3
	s_add_i32 s92, s92, s95
	s_mov_b32 s94, 0x10000
	s_cmpk_lt_u32 s92, 0x80
	s_cbranch_scc1 .Lcv1_heavy
	s_addk_i32 s92, 384
	s_lshl_b32 s95, s92, 9
	s_branch .Lcv1_go
